# nt hint also on the residual rows read by the gemm_out epilogue and the phase-0 GEMV / Fourier-fold weight loads
# baseline (speedup 1.0000x reference)
; DI void phase0(const Params& P, char* smem) {
;     ...
;       const float* w = P.w_mod + ((size_t)l * 1024 + kq * 256) * 6144 + col0 + col;
; #pragma unroll 16
;       for (int k = 0; k < 256; k++) {
;         float wv = w[(size_t)k * 6144];
; #pragma unroll
;         for (int n = 0; n < 9; n++) acc[n] += scond[n * 1024 + kq * 256 + k] * wv;
;       }
.LBB0_108:
	v_lshl_add_u64 v[8:9], v[6:7], 0, s[48:49]
	s_mov_b64 s[100:101], 0x6000
	v_mov_b32_e32 v186, v8
	v_mov_b32_e32 v187, v9
	global_load_dword v188, v[8:9], off nt
	v_lshl_add_u64 v[186:187], v[186:187], 0, s[100:101]
	global_load_dword v189, v[186:187], off nt
	v_lshl_add_u64 v[186:187], v[186:187], 0, s[100:101]
	global_load_dword v190, v[186:187], off nt
	v_lshl_add_u64 v[186:187], v[186:187], 0, s[100:101]
	global_load_dword v191, v[186:187], off nt
	v_lshl_add_u64 v[186:187], v[186:187], 0, s[100:101]
	global_load_dword v192, v[186:187], off nt
	v_lshl_add_u64 v[186:187], v[186:187], 0, s[100:101]
	global_load_dword v193, v[186:187], off nt
	v_lshl_add_u64 v[186:187], v[186:187], 0, s[100:101]
	global_load_dword v194, v[186:187], off nt
	v_lshl_add_u64 v[186:187], v[186:187], 0, s[100:101]
	global_load_dword v195, v[186:187], off nt
	v_lshl_add_u64 v[186:187], v[186:187], 0, s[100:101]
	global_load_dword v196, v[186:187], off nt
	v_lshl_add_u64 v[186:187], v[186:187], 0, s[100:101]
	global_load_dword v197, v[186:187], off nt
	v_lshl_add_u64 v[186:187], v[186:187], 0, s[100:101]
	global_load_dword v198, v[186:187], off nt
	v_lshl_add_u64 v[186:187], v[186:187], 0, s[100:101]
	global_load_dword v199, v[186:187], off nt
	v_lshl_add_u64 v[186:187], v[186:187], 0, s[100:101]
	global_load_dword v200, v[186:187], off nt
	v_lshl_add_u64 v[186:187], v[186:187], 0, s[100:101]
	global_load_dword v201, v[186:187], off nt
	v_lshl_add_u64 v[186:187], v[186:187], 0, s[100:101]
	global_load_dword v202, v[186:187], off nt
	v_lshl_add_u64 v[186:187], v[186:187], 0, s[100:101]
	global_load_dword v203, v[186:187], off nt
	ds_read_b128 v[154:157], v69
	ds_read_b128 v[158:161], v69 offset:16
	ds_read_b128 v[126:129], v69 offset:32
	ds_read_b128 v[122:125], v69 offset:48
	ds_read_b128 v[132:135], v69 offset:4096
	s_waitcnt lgkmcnt(4)
	v_mov_b32_e32 v136, v154
	v_add_co_u32_e32 v152, vcc, s23, v8
	s_mov_b32 s28, 0xc000
	s_waitcnt lgkmcnt(0)
	v_mov_b32_e32 v137, v132
	v_addc_co_u32_e32 v153, vcc, 0, v9, vcc
	v_mov_b32_e32 v132, v155
	s_add_u32 s48, s48, 0x60000
	s_addc_u32 s49, s49, 0
	s_cmp_eq_u32 s48, 0x600000
	s_waitcnt vmcnt(15)
	v_mov_b32_e32 v20, v188
	v_pk_fma_f32 v[144:145], v[20:21], v[136:137], v[96:97] op_sel_hi:[0,1,1]
	ds_read_b128 v[162:165], v69 offset:8192
	ds_read_b128 v[136:139], v69 offset:12288
	s_waitcnt lgkmcnt(1)
	v_mov_b32_e32 v96, v162
	s_waitcnt lgkmcnt(0)
	v_mov_b32_e32 v97, v136
	v_pk_fma_f32 v[146:147], v[20:21], v[96:97], v[98:99] op_sel_hi:[0,1,1]
	ds_read_b128 v[166:169], v69 offset:16384
	ds_read_b128 v[96:99], v69 offset:20480
	v_mov_b32_e32 v136, v163
	s_waitcnt lgkmcnt(1)
	v_mov_b32_e32 v140, v166
	s_waitcnt lgkmcnt(0)
	v_mov_b32_e32 v141, v96
	v_pk_fma_f32 v[148:149], v[20:21], v[140:141], v[94:95] op_sel_hi:[0,1,1]
	ds_read_b128 v[174:177], v69 offset:24576
	ds_read_b128 v[140:143], v69 offset:28672
	v_mov_b32_e32 v96, v167
	s_waitcnt lgkmcnt(1)
	v_mov_b32_e32 v94, v174
	s_waitcnt lgkmcnt(0)
	v_mov_b32_e32 v95, v140
	v_pk_fma_f32 v[150:151], v[20:21], v[94:95], v[92:93] op_sel_hi:[0,1,1]
	ds_read_b128 v[92:95], v69 offset:32768
	v_mov_b32_e32 v140, v175
	s_waitcnt lgkmcnt(0)
	v_fmac_f32_e32 v71, v20, v92
	v_add_co_u32_e32 v92, vcc, s28, v8
	s_mov_b32 s28, 0x12000
	s_waitcnt vmcnt(14)
	v_mov_b32_e32 v20, v189
	v_fmac_f32_e32 v71, v20, v93
	v_addc_co_u32_e32 v93, vcc, 0, v9, vcc
	v_pk_fma_f32 v[132:133], v[20:21], v[132:133], v[144:145] op_sel_hi:[0,1,1]
	v_pk_fma_f32 v[136:137], v[20:21], v[136:137], v[146:147] op_sel_hi:[0,1,1]
	v_pk_fma_f32 v[96:97], v[20:21], v[96:97], v[148:149] op_sel_hi:[0,1,1]
	v_pk_fma_f32 v[140:141], v[20:21], v[140:141], v[150:151] op_sel_hi:[0,1,1]
	v_mov_b32_e32 v92, v156
	v_mov_b32_e32 v93, v134
	v_mov_b32_e32 v134, v157
	s_waitcnt vmcnt(13)
	v_mov_b32_e32 v20, v190
	v_pk_fma_f32 v[92:93], v[20:21], v[92:93], v[132:133] op_sel_hi:[0,1,1]
	v_mov_b32_e32 v132, v164
	v_mov_b32_e32 v133, v138
	v_pk_fma_f32 v[132:133], v[20:21], v[132:133], v[136:137] op_sel_hi:[0,1,1]
	v_mov_b32_e32 v136, v168
	v_mov_b32_e32 v137, v98
	v_pk_fma_f32 v[96:97], v[20:21], v[136:137], v[96:97] op_sel_hi:[0,1,1]
	v_mov_b32_e32 v136, v176
	v_mov_b32_e32 v137, v142
	v_pk_fma_f32 v[136:137], v[20:21], v[136:137], v[140:141] op_sel_hi:[0,1,1]
	v_add_co_u32_e32 v140, vcc, s28, v8
	v_fmac_f32_e32 v71, v20, v94
	s_nop 0
	v_addc_co_u32_e32 v141, vcc, 0, v9, vcc
	v_mov_b32_e32 v138, v165
	v_mov_b32_e32 v98, v169
	v_mov_b32_e32 v142, v177
	s_mov_b32 s28, 0x1e000
	s_waitcnt vmcnt(12)
	v_mov_b32_e32 v20, v191
	v_pk_fma_f32 v[134:135], v[20:21], v[134:135], v[92:93] op_sel_hi:[0,1,1]
	v_add_co_u32_e32 v92, vcc, s27, v8
	v_pk_fma_f32 v[132:133], v[20:21], v[138:139], v[132:133] op_sel_hi:[0,1,1]
	s_nop 0
	v_addc_co_u32_e32 v93, vcc, 0, v9, vcc
	v_pk_fma_f32 v[138:139], v[20:21], v[98:99], v[96:97] op_sel_hi:[0,1,1]
	v_pk_fma_f32 v[140:141], v[20:21], v[142:143], v[136:137] op_sel_hi:[0,1,1]
	v_fmac_f32_e32 v71, v20, v95
	ds_read_b128 v[92:95], v69 offset:4112
	v_mov_b32_e32 v96, v158
	v_add_co_u32_e32 v152, vcc, s28, v8
	s_mov_b32 s28, 0x24000
	s_waitcnt lgkmcnt(0)
	v_mov_b32_e32 v97, v92
	v_addc_co_u32_e32 v153, vcc, 0, v9, vcc
	v_mov_b32_e32 v92, v159
	s_waitcnt vmcnt(11)
	v_mov_b32_e32 v20, v192
	v_pk_fma_f32 v[144:145], v[20:21], v[96:97], v[134:135] op_sel_hi:[0,1,1]
	ds_read_b128 v[154:157], v69 offset:8208
	ds_read_b128 v[96:99], v69 offset:12304
	s_waitcnt lgkmcnt(1)
	v_mov_b32_e32 v134, v154
	s_waitcnt lgkmcnt(0)
	v_mov_b32_e32 v135, v96
	v_pk_fma_f32 v[146:147], v[20:21], v[134:135], v[132:133] op_sel_hi:[0,1,1]
	ds_read_b128 v[162:165], v69 offset:16400
	ds_read_b128 v[132:135], v69 offset:20496
	v_mov_b32_e32 v96, v155
	s_waitcnt lgkmcnt(1)
; DI void phase0(const Params& P, char* smem) {
;     ...
;       for (int k = 0; k < 256; k++) {
;         float wv = w[(size_t)k * 6144];
; #pragma unroll
;         for (int n = 0; n < 9; n++) acc[n] += scond[n * 1024 + kq * 256 + k] * wv;
	v_mov_b32_e32 v136, v162
	s_waitcnt lgkmcnt(0)
	v_mov_b32_e32 v137, v132
	v_pk_fma_f32 v[148:149], v[20:21], v[136:137], v[138:139] op_sel_hi:[0,1,1]
	ds_read_b128 v[166:169], v69 offset:24592
	ds_read_b128 v[136:139], v69 offset:28688
	v_mov_b32_e32 v132, v163
	s_waitcnt lgkmcnt(1)
	v_mov_b32_e32 v142, v166
	s_waitcnt lgkmcnt(0)
	v_mov_b32_e32 v143, v136
	v_pk_fma_f32 v[150:151], v[20:21], v[142:143], v[140:141] op_sel_hi:[0,1,1]
	ds_read_b128 v[140:143], v69 offset:32784
	v_mov_b32_e32 v136, v167
	s_waitcnt lgkmcnt(0)
	v_fmac_f32_e32 v71, v20, v140
	v_add_co_u32_e32 v140, vcc, s28, v8
	s_mov_b32 s28, 0x2a000
	s_waitcnt vmcnt(10)
	v_mov_b32_e32 v20, v193
	v_fmac_f32_e32 v71, v20, v141
	v_addc_co_u32_e32 v141, vcc, 0, v9, vcc
	v_pk_fma_f32 v[92:93], v[20:21], v[92:93], v[144:145] op_sel_hi:[0,1,1]
	v_pk_fma_f32 v[96:97], v[20:21], v[96:97], v[146:147] op_sel_hi:[0,1,1]
	v_pk_fma_f32 v[132:133], v[20:21], v[132:133], v[148:149] op_sel_hi:[0,1,1]
	v_pk_fma_f32 v[136:137], v[20:21], v[136:137], v[150:151] op_sel_hi:[0,1,1]
	v_mov_b32_e32 v140, v160
	v_mov_b32_e32 v141, v94
	v_mov_b32_e32 v94, v161
	s_waitcnt vmcnt(9)
	v_mov_b32_e32 v20, v194
	v_pk_fma_f32 v[92:93], v[20:21], v[140:141], v[92:93] op_sel_hi:[0,1,1]
	v_mov_b32_e32 v140, v156
	v_mov_b32_e32 v141, v98
	v_pk_fma_f32 v[96:97], v[20:21], v[140:141], v[96:97] op_sel_hi:[0,1,1]
	v_mov_b32_e32 v140, v164
	v_mov_b32_e32 v141, v134
	v_pk_fma_f32 v[132:133], v[20:21], v[140:141], v[132:133] op_sel_hi:[0,1,1]
	v_mov_b32_e32 v140, v168
	v_mov_b32_e32 v141, v138
	v_pk_fma_f32 v[136:137], v[20:21], v[140:141], v[136:137] op_sel_hi:[0,1,1]
	v_add_co_u32_e32 v140, vcc, s28, v8
	v_fmac_f32_e32 v71, v20, v142
	s_nop 0
	v_addc_co_u32_e32 v141, vcc, 0, v9, vcc
	s_mov_b32 s28, 0x30000
	v_mov_b32_e32 v98, v157
	v_mov_b32_e32 v134, v165
	v_mov_b32_e32 v138, v169
	s_waitcnt vmcnt(8)
	v_mov_b32_e32 v20, v195
	v_pk_fma_f32 v[140:141], v[20:21], v[94:95], v[92:93] op_sel_hi:[0,1,1]
	v_add_co_u32_e32 v92, vcc, s28, v8
	v_pk_fma_f32 v[144:145], v[20:21], v[98:99], v[96:97] op_sel_hi:[0,1,1]
	s_nop 0
	v_addc_co_u32_e32 v93, vcc, 0, v9, vcc
	v_pk_fma_f32 v[146:147], v[20:21], v[134:135], v[132:133] op_sel_hi:[0,1,1]
	v_pk_fma_f32 v[148:149], v[20:21], v[138:139], v[136:137] op_sel_hi:[0,1,1]
	v_fmac_f32_e32 v71, v20, v143
	ds_read_b128 v[92:95], v69 offset:4128
	v_mov_b32_e32 v96, v126
	s_mov_b32 s28, 0x36000
	v_add_co_u32_e32 v152, vcc, s28, v8
	s_waitcnt lgkmcnt(0)
	v_mov_b32_e32 v97, v92
	v_addc_co_u32_e32 v153, vcc, 0, v9, vcc
	s_mov_b32 s28, 0x3c000
	v_mov_b32_e32 v92, v127
	s_waitcnt vmcnt(7)
	v_mov_b32_e32 v20, v196
	v_pk_fma_f32 v[150:151], v[20:21], v[96:97], v[140:141] op_sel_hi:[0,1,1]
	ds_read_b128 v[154:157], v69 offset:8224
	ds_read_b128 v[96:99], v69 offset:12320
	s_waitcnt lgkmcnt(1)
	v_mov_b32_e32 v132, v154
	s_waitcnt lgkmcnt(0)
	v_mov_b32_e32 v133, v96
	v_pk_fma_f32 v[144:145], v[20:21], v[132:133], v[144:145] op_sel_hi:[0,1,1]
	ds_read_b128 v[158:161], v69 offset:16416
	ds_read_b128 v[132:135], v69 offset:20512
	v_mov_b32_e32 v96, v155
	s_waitcnt lgkmcnt(1)
	v_mov_b32_e32 v136, v158
	s_waitcnt lgkmcnt(0)
	v_mov_b32_e32 v137, v132
	v_pk_fma_f32 v[146:147], v[20:21], v[136:137], v[146:147] op_sel_hi:[0,1,1]
	ds_read_b128 v[162:165], v69 offset:24608
	ds_read_b128 v[136:139], v69 offset:28704
	v_mov_b32_e32 v132, v159
	s_waitcnt lgkmcnt(1)
	v_mov_b32_e32 v140, v162
	s_waitcnt lgkmcnt(0)
	v_mov_b32_e32 v141, v136
	v_pk_fma_f32 v[148:149], v[20:21], v[140:141], v[148:149] op_sel_hi:[0,1,1]
	ds_read_b128 v[140:143], v69 offset:32800
	v_mov_b32_e32 v136, v163
	s_waitcnt lgkmcnt(0)
	v_fmac_f32_e32 v71, v20, v140
	s_waitcnt vmcnt(6)
	v_mov_b32_e32 v20, v197
	v_pk_fma_f32 v[126:127], v[20:21], v[132:133], v[146:147] op_sel_hi:[0,1,1]
	v_pk_fma_f32 v[132:133], v[20:21], v[136:137], v[148:149] op_sel_hi:[0,1,1]
	v_add_co_u32_e32 v136, vcc, s28, v8
	v_pk_fma_f32 v[92:93], v[20:21], v[92:93], v[150:151] op_sel_hi:[0,1,1]
	s_nop 0
	v_addc_co_u32_e32 v137, vcc, 0, v9, vcc
	v_pk_fma_f32 v[96:97], v[20:21], v[96:97], v[144:145] op_sel_hi:[0,1,1]
	v_fmac_f32_e32 v71, v20, v141
	v_mov_b32_e32 v136, v128
	v_mov_b32_e32 v137, v94
	s_mov_b32 s28, 0x42000
	v_mov_b32_e32 v94, v129
	s_waitcnt vmcnt(5)
	v_mov_b32_e32 v20, v198
	v_pk_fma_f32 v[92:93], v[20:21], v[136:137], v[92:93] op_sel_hi:[0,1,1]
	v_mov_b32_e32 v136, v156
	v_mov_b32_e32 v137, v98
	v_pk_fma_f32 v[96:97], v[20:21], v[136:137], v[96:97] op_sel_hi:[0,1,1]
	v_mov_b32_e32 v136, v160
	v_mov_b32_e32 v137, v134
	v_pk_fma_f32 v[126:127], v[20:21], v[136:137], v[126:127] op_sel_hi:[0,1,1]
	v_mov_b32_e32 v136, v164
	v_mov_b32_e32 v137, v138
	v_pk_fma_f32 v[132:133], v[20:21], v[136:137], v[132:133] op_sel_hi:[0,1,1]
	v_add_co_u32_e32 v136, vcc, s28, v8
	v_fmac_f32_e32 v71, v20, v142
	s_nop 0
	v_addc_co_u32_e32 v137, vcc, 0, v9, vcc
	s_mov_b32 s28, 0x48000
	v_mov_b32_e32 v98, v157
	v_mov_b32_e32 v134, v161
	v_mov_b32_e32 v138, v165
	s_waitcnt vmcnt(4)
; DI void phase0(const Params& P, char* smem) {
;     ...
;       for (int k = 0; k < 256; k++) {
;         float wv = w[(size_t)k * 6144];
; #pragma unroll
;         for (int n = 0; n < 9; n++) acc[n] += scond[n * 1024 + kq * 256 + k] * wv;
;       }
; #pragma unroll
;       for (int n = 0; n < 9; n++) red[(kq * 9 + n) * 64 + col] = acc[n];
;       __syncthreads();
;       for (int idx = tid; idx < 576; idx += 256) {
;         int n = idx / 64, cc = idx % 64;
;         float s = red[(0 * 9 + n) * 64 + cc] + red[(1 * 9 + n) * 64 + cc] + red[(2 * 9 + n) * 64 + cc] + red[(3 * 9 + n) * 64 + cc];
;         P.mod[(size_t)(l * 9 + n) * 6144 + col0 + cc] = s + P.b_mod[l * 6144 + col0 + cc];
	v_mov_b32_e32 v20, v199
	v_pk_fma_f32 v[128:129], v[20:21], v[94:95], v[92:93] op_sel_hi:[0,1,1]
	v_add_co_u32_e32 v92, vcc, s28, v8
	v_pk_fma_f32 v[136:137], v[20:21], v[98:99], v[96:97] op_sel_hi:[0,1,1]
	s_nop 0
	v_addc_co_u32_e32 v93, vcc, 0, v9, vcc
	v_pk_fma_f32 v[134:135], v[20:21], v[134:135], v[126:127] op_sel_hi:[0,1,1]
	v_pk_fma_f32 v[138:139], v[20:21], v[138:139], v[132:133] op_sel_hi:[0,1,1]
	v_fmac_f32_e32 v71, v20, v143
	ds_read_b128 v[92:95], v69 offset:4144
	v_mov_b32_e32 v96, v122
	s_mov_b32 s28, 0x4e000
	v_add_co_u32_e32 v148, vcc, s28, v8
	s_waitcnt lgkmcnt(0)
	v_mov_b32_e32 v97, v92
	v_addc_co_u32_e32 v149, vcc, 0, v9, vcc
	s_mov_b32 s28, 0x54000
	v_mov_b32_e32 v92, v123
	s_waitcnt vmcnt(3)
	v_mov_b32_e32 v20, v200
	v_pk_fma_f32 v[140:141], v[20:21], v[96:97], v[128:129] op_sel_hi:[0,1,1]
	ds_read_b128 v[150:153], v69 offset:8240
	ds_read_b128 v[96:99], v69 offset:12336
	s_waitcnt lgkmcnt(1)
	v_mov_b32_e32 v126, v150
	s_waitcnt lgkmcnt(0)
	v_mov_b32_e32 v127, v96
	v_pk_fma_f32 v[142:143], v[20:21], v[126:127], v[136:137] op_sel_hi:[0,1,1]
	ds_read_b128 v[154:157], v69 offset:16432
	ds_read_b128 v[126:129], v69 offset:20528
	v_mov_b32_e32 v96, v151
	s_waitcnt lgkmcnt(1)
	v_mov_b32_e32 v132, v154
	s_waitcnt lgkmcnt(0)
	v_mov_b32_e32 v133, v126
	v_pk_fma_f32 v[144:145], v[20:21], v[132:133], v[134:135] op_sel_hi:[0,1,1]
	ds_read_b128 v[158:161], v69 offset:24624
	ds_read_b128 v[132:135], v69 offset:28720
	v_mov_b32_e32 v126, v155
	s_waitcnt lgkmcnt(1)
	v_mov_b32_e32 v136, v158
	s_waitcnt lgkmcnt(0)
	v_mov_b32_e32 v137, v132
	v_pk_fma_f32 v[146:147], v[20:21], v[136:137], v[138:139] op_sel_hi:[0,1,1]
	ds_read_b128 v[136:139], v69 offset:32816
	v_mov_b32_e32 v132, v159
	v_add_u32_e32 v69, 64, v69
	s_waitcnt lgkmcnt(0)
	v_fmac_f32_e32 v71, v20, v136
	s_waitcnt vmcnt(2)
	v_mov_b32_e32 v20, v201
	v_pk_fma_f32 v[122:123], v[20:21], v[126:127], v[144:145] op_sel_hi:[0,1,1]
	v_pk_fma_f32 v[126:127], v[20:21], v[132:133], v[146:147] op_sel_hi:[0,1,1]
	v_add_co_u32_e32 v132, vcc, s28, v8
	v_pk_fma_f32 v[92:93], v[20:21], v[92:93], v[140:141] op_sel_hi:[0,1,1]
	s_nop 0
	v_addc_co_u32_e32 v133, vcc, 0, v9, vcc
	v_pk_fma_f32 v[96:97], v[20:21], v[96:97], v[142:143] op_sel_hi:[0,1,1]
	v_fmac_f32_e32 v71, v20, v137
	s_mov_b32 s28, 0x5a000
	v_add_co_u32_e32 v8, vcc, s28, v8
	s_nop 1
	v_addc_co_u32_e32 v9, vcc, 0, v9, vcc
	v_mov_b32_e32 v132, v124
	v_mov_b32_e32 v133, v94
	v_mov_b32_e32 v94, v125
	s_waitcnt vmcnt(1)
	v_mov_b32_e32 v20, v202
	v_pk_fma_f32 v[92:93], v[20:21], v[132:133], v[92:93] op_sel_hi:[0,1,1]
	v_mov_b32_e32 v132, v152
	v_mov_b32_e32 v133, v98
	v_pk_fma_f32 v[132:133], v[20:21], v[132:133], v[96:97] op_sel_hi:[0,1,1]
	v_mov_b32_e32 v96, v156
	v_mov_b32_e32 v97, v128
	v_pk_fma_f32 v[122:123], v[20:21], v[96:97], v[122:123] op_sel_hi:[0,1,1]
	v_mov_b32_e32 v96, v160
	v_mov_b32_e32 v97, v134
	v_pk_fma_f32 v[126:127], v[20:21], v[96:97], v[126:127] op_sel_hi:[0,1,1]
	v_fmac_f32_e32 v71, v20, v138
	v_mov_b32_e32 v98, v153
	v_mov_b32_e32 v128, v157
	v_mov_b32_e32 v134, v161
	s_waitcnt vmcnt(0)
	v_mov_b32_e32 v8, v203
	v_pk_fma_f32 v[96:97], v[8:9], v[94:95], v[92:93] op_sel_hi:[0,1,1]
	v_pk_fma_f32 v[98:99], v[8:9], v[98:99], v[132:133] op_sel_hi:[0,1,1]
	v_pk_fma_f32 v[94:95], v[8:9], v[128:129], v[122:123] op_sel_hi:[0,1,1]
	v_pk_fma_f32 v[92:93], v[8:9], v[134:135], v[126:127] op_sel_hi:[0,1,1]
	v_fmac_f32_e32 v71, v8, v139
	s_cbranch_scc0 .LBB0_108
	v_readlane_b32 s4, v255, 42
	v_readlane_b32 s5, v255, 43
	ds_write2st64_b32 v118, v96, v97 offset0:144 offset1:145
	ds_write2st64_b32 v118, v98, v99 offset0:146 offset1:147
	ds_write2st64_b32 v118, v94, v95 offset0:148 offset1:149
	ds_write2st64_b32 v118, v92, v93 offset0:150 offset1:151
	ds_write_b32 v118, v71 offset:38912
	s_waitcnt lgkmcnt(0)
	s_barrier
	s_and_saveexec_b64 s[46:47], s[4:5]
	s_cbranch_execz .LBB0_112
	s_and_b64 s[28:29], s[0:1], exec
	s_cselect_b32 s28, 0x1800, 0
	s_add_i32 s28, s78, s28
	s_and_b64 s[0:1], s[0:1], exec
	s_cselect_b32 s29, 9, 0
	s_lshl_b64 s[0:1], s[78:79], 2
	v_readlane_b32 s48, v253, 59
	v_readlane_b32 s49, v253, 60
	s_add_u32 s0, s48, s0
	s_addc_u32 s1, s49, s1
	s_mov_b64 s[48:49], 0
	v_mov_b32_e32 v6, v107
	v_mov_b32_e32 v7, v12

; DI void phase0(const Params& P, char* smem) {
;     ...
;       int f = t - NT, l = f / 64, r = f % 64, kt = r / 4, g = r % 4;
;       float* cst = tile + 64 * 65; float* snt = cst + 64;
;       const float* src = P.w_in + (size_t)l * 1024 * 2304 + (size_t)kt * 64 * 2304 + g * 64;
;       { int n = tid & 63, kq = tid >> 6;
;         for (int i = 0; i < 16; i++) { int k = i * 4 + kq; tile[k * 65 + n] = src[(size_t)k * 2304 + n]; } }
;       if (tid < 64) { float s, c; sincospif((float)tid / 32.f, &s, &c); cst[tid] = c; snt[tid] = s; }
;       __syncthreads();
;       int k = tid & 63, jq = tid >> 6;
;       half_t* o = P.WtIn + (size_t)l * NIN * 1024 + kt * 64 + k;
.LBB0_114:
	v_readlane_b32 s48, v253, 1
	s_add_i32 s0, s85, 0xffffe680
	v_readlane_b32 s52, v253, 5
	v_readlane_b32 s53, v253, 6
	s_lshr_b32 s46, s0, 6
	v_readlane_b32 s49, v253, 2
	v_readlane_b32 s50, v253, 3
	v_readlane_b32 s51, v253, 4
	s_mov_b64 s[76:77], s[52:53]
	s_bfe_u32 s29, s85, 0x40002
	s_mul_i32 s1, s46, 0x900000
	s_mov_b64 s[72:73], s[48:49]
	s_mul_hi_u32 s0, s46, 0x900000
	s_add_u32 s1, s72, s1
	s_addc_u32 s0, s73, s0
	s_mul_i32 s28, s29, 0x90000
	s_add_u32 s1, s1, s28
	s_addc_u32 s47, s0, 0
	s_lshl_b32 s0, s85, 6
	s_and_b32 s28, s0, 0xc0
	s_lshl_b32 s0, s28, 2
	s_add_u32 s0, s1, s0
	s_addc_u32 s1, s47, 0
	v_lshlrev_b32_e32 v20, 2, v16
	v_lshl_add_u64 v[6:7], s[0:1], 0, v[20:21]
	v_readlane_b32 s54, v253, 7
	v_readlane_b32 s55, v253, 8
	v_readlane_b32 s56, v253, 9
	v_readlane_b32 s57, v253, 10
	v_readlane_b32 s58, v253, 11
	v_readlane_b32 s59, v253, 12
	v_readlane_b32 s60, v253, 13
	v_readlane_b32 s61, v253, 14
	v_readlane_b32 s62, v253, 15
	v_readlane_b32 s63, v253, 16
	s_mov_b64 s[74:75], s[50:51]
	v_lshl_add_u64 v[186:187], v[6:7], 0, v[26:27]
	global_load_dword v188, v[186:187], off nt
	v_lshl_add_u64 v[186:187], v[6:7], 0, v[28:29]
	global_load_dword v189, v[186:187], off nt
	v_lshl_add_u64 v[186:187], v[6:7], 0, v[30:31]
	global_load_dword v190, v[186:187], off nt
	v_lshl_add_u64 v[186:187], v[6:7], 0, v[32:33]
	global_load_dword v191, v[186:187], off nt
	v_lshl_add_u64 v[186:187], v[6:7], 0, v[34:35]
	global_load_dword v192, v[186:187], off nt
	v_lshl_add_u64 v[186:187], v[6:7], 0, v[36:37]
	global_load_dword v193, v[186:187], off nt
	v_lshl_add_u64 v[186:187], v[6:7], 0, v[38:39]
	global_load_dword v194, v[186:187], off nt
	v_lshl_add_u64 v[186:187], v[6:7], 0, v[40:41]
	global_load_dword v195, v[186:187], off nt
	v_lshl_add_u64 v[186:187], v[6:7], 0, v[42:43]
	global_load_dword v196, v[186:187], off nt
	v_lshl_add_u64 v[186:187], v[6:7], 0, v[44:45]
	global_load_dword v197, v[186:187], off nt
	v_lshl_add_u64 v[186:187], v[6:7], 0, v[46:47]
	global_load_dword v198, v[186:187], off nt
	v_lshl_add_u64 v[186:187], v[6:7], 0, v[48:49]
	global_load_dword v199, v[186:187], off nt
	v_lshl_add_u64 v[186:187], v[6:7], 0, v[50:51]
	global_load_dword v200, v[186:187], off nt
	v_lshl_add_u64 v[186:187], v[6:7], 0, v[52:53]
	global_load_dword v201, v[186:187], off nt
	v_lshl_add_u64 v[186:187], v[6:7], 0, v[54:55]
	global_load_dword v202, v[186:187], off nt
	v_lshl_add_u64 v[186:187], v[6:7], 0, v[56:57]
	global_load_dword v203, v[186:187], off nt
	s_waitcnt vmcnt(15)
	ds_write_b32 v119, v188
	s_waitcnt vmcnt(14)
	ds_write_b32 v119, v189 offset:1040
	s_waitcnt vmcnt(13)
	ds_write_b32 v119, v190 offset:2080
	s_waitcnt vmcnt(12)
	ds_write_b32 v119, v191 offset:3120
	s_waitcnt vmcnt(11)
	ds_write_b32 v119, v192 offset:4160
	s_waitcnt vmcnt(10)
	ds_write_b32 v119, v193 offset:5200
	s_waitcnt vmcnt(9)
	ds_write_b32 v119, v194 offset:6240
	s_waitcnt vmcnt(8)
	ds_write_b32 v119, v195 offset:7280
	s_waitcnt vmcnt(7)
	ds_write_b32 v119, v196 offset:8320
	s_waitcnt vmcnt(6)
	ds_write_b32 v119, v197 offset:9360
	s_waitcnt vmcnt(5)
	ds_write_b32 v119, v198 offset:10400
	s_waitcnt vmcnt(4)
	ds_write_b32 v119, v199 offset:11440
	s_waitcnt vmcnt(3)
	ds_write_b32 v119, v200 offset:12480
	s_waitcnt vmcnt(2)
	ds_write_b32 v119, v201 offset:13520
	s_waitcnt vmcnt(1)
	ds_write_b32 v119, v202 offset:14560
	s_waitcnt vmcnt(0)
	ds_write_b32 v119, v203 offset:15600
	s_and_saveexec_b64 s[0:1], s[10:11]
	ds_write2st64_b32 v14, v23, v25 offset0:65 offset1:66
	s_or_b64 exec, exec, s[0:1]
	s_mul_hi_u32 s0, s46, 0x500000
	s_mul_i32 s46, s46, 0x500000
	s_add_u32 s1, s90, s46
	s_addc_u32 s46, s91, s0
	s_lshl_b32 s0, s29, 7
	s_add_u32 s0, s1, s0
	s_addc_u32 s1, s46, 0
	v_lshlrev_b32_e32 v20, 1, v16
	v_readlane_b32 s56, v255, 3
	v_lshl_add_u64 v[6:7], s[0:1], 0, v[20:21]
	s_or_b32 s0, s28, 0x100
	s_mov_b32 s1, 0
	v_mov_b32_e32 v20, v114
	v_mov_b32_e32 v69, v113
	v_mov_b32_e32 v71, v112
	v_mov_b32_e32 v73, v111
	v_mov_b32_e32 v75, v110
	v_mov_b32_e32 v92, v109
	v_mov_b32_e32 v93, v108
	v_mov_b32_e32 v94, v100
	v_readlane_b32 s58, v255, 5
	v_readlane_b32 s59, v255, 6
	v_readlane_b32 s62, v255, 9
	v_readlane_b32 s63, v255, 10
	v_readlane_b32 s64, v255, 11
	v_readlane_b32 s65, v255, 12
	v_readlane_b32 s66, v255, 13
	v_readlane_b32 s67, v255, 14
	s_mov_b32 s72, 0x3c800000
	s_mov_b32 s74, 0x3db504f3
	s_waitcnt lgkmcnt(0)
	s_barrier
	v_readlane_b32 s57, v255, 4
	v_readlane_b32 s60, v255, 7
	v_readlane_b32 s61, v255, 8
	v_readlane_b32 s68, v255, 15
	v_readlane_b32 s69, v255, 16
	v_readlane_b32 s70, v255, 17
	v_readlane_b32 s71, v255, 18

; DI void gemm_out_phase(const Params& P, int l, char* smem) {
;     ...
;     const int r0 = (mt + mt0) * 256 + wr2 * 128;
;     const int n = row_mod(r0);
;     const int cbase = nt * 128 + wc2 * 64;
;     const float* res; float* dst;
;     if (r0 < TC) { res = P.ctx + (size_t)r0 * D; dst = P.xcbuf + (size_t)r0 * D; }
;     else { dst = P.out + (size_t)(r0 - TC) * D; res = l == 0 ? P.x + (size_t)(r0 - TC) * D : dst; }
;     res += cbase + fr2 * 4; dst += cbase + fr2 * 4;
;     const float4 g4 = *(const float4*)(P.mod + (size_t)(l * 9 + n) * 6144 + 2 * 1024 + cbase + fr2 * 4);
;     float4 rres[4][8];
; #pragma unroll
;     for (int q = 0; q < 4; q++)
; #pragma unroll
;       for (int i = 0; i < 8; i++) rres[q][i] = *(const float4*)(res + (size_t)(q * 32 + i * 4 + fq2) * D);
.LBB0_527:
	s_or_b64 exec, exec, s[0:1]
	v_lshrrev_b32_e32 v2, 13, v148
	v_cndmask_b32_e64 v3, v2, 8, vcc
	s_lshl_b32 s0, s9, 7
	v_and_b32_e32 v152, 15, v150
	v_and_or_b32 v2, v150, 64, s0
	v_add_u32_e32 v3, s89, v3
	v_mov_b64_e32 v[4:5], s[66:67]
	v_lshl_or_b32 v144, v152, 2, v2
	v_mad_u64_u32 v[4:5], s[0:1], v3, s42, v[4:5]
	v_ashrrev_i32_e32 v3, 31, v2
	v_bfe_u32 v151, v150, 4, 2
	v_ashrrev_i32_e32 v145, 31, v144
	v_lshl_add_u64 v[2:3], v[2:3], 2, v[4:5]
	v_lshlrev_b32_e32 v148, 4, v152
	v_lshl_add_u64 v[0:1], v[144:145], 2, v[0:1]
	v_lshl_add_u64 v[2:3], v[2:3], 0, v[148:149]
	v_lshlrev_b32_e32 v142, 12, v151
	v_mov_b32_e32 v143, v149
	s_movk_i32 s0, 0x2000
	v_lshl_add_u64 v[4:5], v[0:1], 0, v[142:143]
	v_add_co_u32_e32 v0, vcc, s0, v2
	s_movk_i32 s0, 0x4000
	s_nop 0
	v_addc_co_u32_e32 v1, vcc, 0, v3, vcc
	v_add_co_u32_e32 v6, vcc, s0, v4
	s_mov_b32 s0, 0x8000
	s_nop 0
	v_addc_co_u32_e32 v7, vcc, 0, v5, vcc
	v_add_co_u32_e32 v8, vcc, s0, v4
	s_mov_b32 s0, 0xc000
	s_nop 0
	v_addc_co_u32_e32 v9, vcc, 0, v5, vcc
	global_load_dwordx4 v[0:3], v[0:1], off nt
	s_nop 0
	global_load_dwordx4 v[128:131], v[4:5], off nt
	global_load_dwordx4 v[124:127], v[6:7], off nt
	global_load_dwordx4 v[120:123], v[8:9], off nt
	v_add_co_u32_e32 v6, vcc, s0, v4
	s_mov_b32 s0, 0x14000
	s_nop 0
	v_addc_co_u32_e32 v7, vcc, 0, v5, vcc
	v_add_co_u32_e32 v8, vcc, s33, v4
	v_lshlrev_b32_e32 v146, 10, v151
	s_nop 0
	v_addc_co_u32_e32 v9, vcc, 0, v5, vcc
	global_load_dwordx4 v[116:119], v[6:7], off nt
	global_load_dwordx4 v[112:115], v[8:9], off nt
	v_add_co_u32_e32 v6, vcc, s0, v4
	s_mov_b32 s0, 0x18000
	s_nop 0
	v_addc_co_u32_e32 v7, vcc, 0, v5, vcc
	v_add_co_u32_e32 v8, vcc, s0, v4
	s_mov_b32 s0, 0x1c000
	s_nop 0
	v_addc_co_u32_e32 v9, vcc, 0, v5, vcc
	global_load_dwordx4 v[108:111], v[6:7], off nt
	global_load_dwordx4 v[104:107], v[8:9], off nt
	v_add_co_u32_e32 v6, vcc, s0, v4
	s_mov_b32 s0, 0x24000
	s_nop 0
	v_addc_co_u32_e32 v7, vcc, 0, v5, vcc
	v_add_co_u32_e32 v8, vcc, s31, v4
	s_nop 1
	v_addc_co_u32_e32 v9, vcc, 0, v5, vcc
	global_load_dwordx4 v[100:103], v[6:7], off nt
	global_load_dwordx4 v[96:99], v[8:9], off nt
	v_add_co_u32_e32 v6, vcc, s0, v4
	s_mov_b32 s0, 0x28000
	s_nop 0
	v_addc_co_u32_e32 v7, vcc, 0, v5, vcc
	v_add_co_u32_e32 v8, vcc, s0, v4
	s_mov_b32 s0, 0x2c000
	s_nop 0
	v_addc_co_u32_e32 v9, vcc, 0, v5, vcc
	global_load_dwordx4 v[92:95], v[6:7], off nt
	global_load_dwordx4 v[88:91], v[8:9], off nt
	v_add_co_u32_e32 v6, vcc, s0, v4
	s_mov_b32 s0, 0x30000
	s_nop 0
	v_addc_co_u32_e32 v7, vcc, 0, v5, vcc
	v_add_co_u32_e32 v8, vcc, s0, v4
	s_mov_b32 s0, 0x34000
	s_nop 0
	v_addc_co_u32_e32 v9, vcc, 0, v5, vcc
	global_load_dwordx4 v[84:87], v[6:7], off nt
	global_load_dwordx4 v[80:83], v[8:9], off nt
	v_add_co_u32_e32 v6, vcc, s0, v4
	s_mov_b32 s0, 0x38000
	s_nop 0
	v_addc_co_u32_e32 v7, vcc, 0, v5, vcc
	v_add_co_u32_e32 v8, vcc, s0, v4
	s_mov_b32 s0, 0x3c000
	s_nop 0
	v_addc_co_u32_e32 v9, vcc, 0, v5, vcc
	global_load_dwordx4 v[76:79], v[6:7], off nt
	global_load_dwordx4 v[72:75], v[8:9], off nt
	v_add_co_u32_e32 v6, vcc, s0, v4
	s_mov_b32 s0, 0x44000
	s_nop 0
	v_addc_co_u32_e32 v7, vcc, 0, v5, vcc
	v_add_co_u32_e32 v8, vcc, s88, v4
	s_nop 1
	v_addc_co_u32_e32 v9, vcc, 0, v5, vcc
	global_load_dwordx4 v[68:71], v[6:7], off nt
	global_load_dwordx4 v[64:67], v[8:9], off nt
	v_add_co_u32_e32 v6, vcc, s0, v4
	s_mov_b32 s0, 0x48000
	s_nop 0
	v_addc_co_u32_e32 v7, vcc, 0, v5, vcc
	v_add_co_u32_e32 v8, vcc, s0, v4
	s_mov_b32 s0, 0x4c000
	s_nop 0
	v_addc_co_u32_e32 v9, vcc, 0, v5, vcc
	global_load_dwordx4 v[60:63], v[6:7], off nt
	global_load_dwordx4 v[56:59], v[8:9], off nt
	v_add_co_u32_e32 v6, vcc, s0, v4
	s_mov_b32 s0, 0x50000
	s_nop 0
	v_addc_co_u32_e32 v7, vcc, 0, v5, vcc
	v_add_co_u32_e32 v8, vcc, s0, v4
	s_mov_b32 s0, 0x54000
	s_nop 0
	v_addc_co_u32_e32 v9, vcc, 0, v5, vcc
	global_load_dwordx4 v[52:55], v[6:7], off nt
	global_load_dwordx4 v[48:51], v[8:9], off nt
	v_add_co_u32_e32 v6, vcc, s0, v4
	s_mov_b32 s0, 0x58000
	s_nop 0
	v_addc_co_u32_e32 v7, vcc, 0, v5, vcc
	v_add_co_u32_e32 v8, vcc, s0, v4
	s_mov_b32 s0, 0x5c000
	s_nop 0
	v_addc_co_u32_e32 v9, vcc, 0, v5, vcc
	global_load_dwordx4 v[44:47], v[6:7], off nt
	global_load_dwordx4 v[40:43], v[8:9], off nt
	v_add_co_u32_e32 v6, vcc, s0, v4
	s_mov_b32 s0, 0x60000
	s_nop 0
	v_addc_co_u32_e32 v7, vcc, 0, v5, vcc
	v_add_co_u32_e32 v8, vcc, s0, v4
	s_mov_b32 s0, 0x64000
	s_nop 0
	v_addc_co_u32_e32 v9, vcc, 0, v5, vcc
	global_load_dwordx4 v[36:39], v[6:7], off nt
	global_load_dwordx4 v[32:35], v[8:9], off nt
	v_add_co_u32_e32 v6, vcc, s0, v4
	s_mov_b32 s0, 0x68000
	s_nop 0
	v_addc_co_u32_e32 v7, vcc, 0, v5, vcc
	v_add_co_u32_e32 v8, vcc, s0, v4
	s_mov_b32 s0, 0x6c000
	s_nop 0
	v_addc_co_u32_e32 v9, vcc, 0, v5, vcc
	global_load_dwordx4 v[28:31], v[6:7], off nt
	global_load_dwordx4 v[24:27], v[8:9], off nt
	v_add_co_u32_e32 v6, vcc, s0, v4
	s_mov_b32 s0, 0x70000
	s_nop 0
	v_addc_co_u32_e32 v7, vcc, 0, v5, vcc
	v_add_co_u32_e32 v8, vcc, s0, v4
	s_lshl_b32 s0, s7, 3
	s_nop 0
	v_addc_co_u32_e32 v9, vcc, 0, v5, vcc
	global_load_dwordx4 v[20:23], v[6:7], off nt
	global_load_dwordx4 v[16:19], v[8:9], off nt
	v_add_co_u32_e32 v6, vcc, 0x74000, v4
	s_add_i32 s10, s29, s0
	s_nop 0
	v_addc_co_u32_e32 v7, vcc, 0, v5, vcc
	v_add_co_u32_e32 v8, vcc, 0x78000, v4
	s_nop 1
	v_addc_co_u32_e32 v9, vcc, 0, v5, vcc
	v_add_co_u32_e32 v4, vcc, 0x7c000, v4
	global_load_dwordx4 v[12:15], v[6:7], off nt
	s_nop 0
	global_load_dwordx4 v[8:11], v[8:9], off nt
	v_addc_co_u32_e32 v5, vcc, 0, v5, vcc
	global_load_dwordx4 v[4:7], v[4:5], off nt
	s_branch .LBB0_529
